# out-GEMM epilogue hand-written: residual x loads run 4 row groups ahead with counted vmcnt, batched reductions/atomics (on top of ovfinal)
# speedup vs baseline: 1.0058x; 1.0024x over previous
.LBB0_560:
	v_readlane_b32 s60, v233, 0
	v_readlane_b32 s61, v233, 1
	v_readlane_b32 s62, v233, 2
	v_readlane_b32 s63, v233, 3
	v_readlane_b32 s64, v233, 4
	v_readlane_b32 s65, v233, 5
	v_readlane_b32 s66, v233, 6
	v_readlane_b32 s67, v233, 7
	v_readlane_b32 s68, v233, 8
	v_readlane_b32 s69, v233, 9
	v_readlane_b32 s70, v233, 10
	v_readlane_b32 s71, v233, 11
	v_readlane_b32 s72, v233, 12
	v_readlane_b32 s73, v233, 13
	v_readlane_b32 s74, v233, 14
	v_readlane_b32 s75, v233, 15
	v_lshl_add_u32 v144, s24, 8, v1
	s_and_b32 s96, s24, 0x7f
	s_lshl_b32 s96, s96, 21
	s_cmp_ge_u32 s24, 0x80
	s_cselect_b32 s100, s62, s60
	s_cselect_b32 s101, s63, s61
	s_add_u32 s100, s100, s96
	s_addc_u32 s101, s101, 0
	s_lshl_b32 s96, s24, 20
	s_add_u32 s98, s6, s96
	s_addc_u32 s99, s7, 0
	s_lshl_b32 s96, s24, 10
	s_add_u32 s96, s8, s96
	s_addc_u32 s97, s9, 0
	s_lshl_b32 vcc_lo, s22, 10
	v_lshl_add_u32 v158, v1, 13, vcc_lo
	v_lshl_add_u32 v158, v152, 2, v158
	s_lshl_b32 vcc_lo, s22, 9
	v_lshl_add_u32 v160, v1, 12, vcc_lo
	v_lshl_add_u32 v160, v152, 1, v160
	v_lshlrev_b32_e32 v145, 2, v1
	v_xor_b32_e32 v162, 16, v156
	v_lshlrev_b32_e32 v162, 2, v162
	v_xor_b32_e32 v163, 32, v156
	v_lshlrev_b32_e32 v163, 2, v163
	v_mov_b32_e32 v159, v158
	global_load_dwordx4 v[164:167], v159, s[100:101]
	global_load_dwordx4 v[168:171], v159, s[100:101] offset:64
	global_load_dwordx4 v[172:175], v159, s[100:101] offset:512
	global_load_dwordx4 v[176:179], v159, s[100:101] offset:576
	v_add_u32_e32 v159, 0x20000, v158
	global_load_dwordx4 v[180:183], v159, s[100:101]
	global_load_dwordx4 v[184:187], v159, s[100:101] offset:64
	global_load_dwordx4 v[188:191], v159, s[100:101] offset:512
	global_load_dwordx4 v[192:195], v159, s[100:101] offset:576
	v_add_u32_e32 v159, 0x40000, v158
	global_load_dwordx4 v[196:199], v159, s[100:101]
	global_load_dwordx4 v[200:203], v159, s[100:101] offset:64
	global_load_dwordx4 v[204:207], v159, s[100:101] offset:512
	global_load_dwordx4 v[208:211], v159, s[100:101] offset:576
	v_add_u32_e32 v159, 0x60000, v158
	global_load_dwordx4 v[212:215], v159, s[100:101]
	global_load_dwordx4 v[216:219], v159, s[100:101] offset:64
	global_load_dwordx4 v[220:223], v159, s[100:101] offset:512
	global_load_dwordx4 v[224:227], v159, s[100:101] offset:576
	s_waitcnt vmcnt(12)
	v_mov_b32_e32 v161, v160
	v_pk_add_f32 v[126:127], v[126:127], v[164:165]
	v_pk_add_f32 v[128:129], v[128:129], v[166:167]
	v_cvt_pk_bf16_f32 v164, v126, v127
	v_cvt_pk_bf16_f32 v165, v128, v129
	v_mul_f32_e32 v157, v126, v126
	v_fmac_f32_e32 v157, v127, v127
	v_fmac_f32_e32 v157, v128, v128
	v_fmac_f32_e32 v157, v129, v129
	global_store_dwordx2 v161, v[164:165], s[98:99]
	v_pk_add_f32 v[122:123], v[122:123], v[168:169]
	v_pk_add_f32 v[124:125], v[124:125], v[170:171]
	v_cvt_pk_bf16_f32 v168, v122, v123
	v_cvt_pk_bf16_f32 v169, v124, v125
	v_fmac_f32_e32 v157, v122, v122
	v_fmac_f32_e32 v157, v123, v123
	v_fmac_f32_e32 v157, v124, v124
	v_fmac_f32_e32 v157, v125, v125
	global_store_dwordx2 v161, v[168:169], s[98:99] offset:32
	v_pk_add_f32 v[118:119], v[118:119], v[172:173]
	v_pk_add_f32 v[120:121], v[120:121], v[174:175]
	v_cvt_pk_bf16_f32 v172, v118, v119
	v_cvt_pk_bf16_f32 v173, v120, v121
	v_fmac_f32_e32 v157, v118, v118
	v_fmac_f32_e32 v157, v119, v119
	v_fmac_f32_e32 v157, v120, v120
	v_fmac_f32_e32 v157, v121, v121
	global_store_dwordx2 v161, v[172:173], s[98:99] offset:256
	v_pk_add_f32 v[114:115], v[114:115], v[176:177]
	v_pk_add_f32 v[116:117], v[116:117], v[178:179]
	v_cvt_pk_bf16_f32 v176, v114, v115
	v_cvt_pk_bf16_f32 v177, v116, v117
	v_fmac_f32_e32 v157, v114, v114
	v_fmac_f32_e32 v157, v115, v115
	v_fmac_f32_e32 v157, v116, v116
	v_fmac_f32_e32 v157, v117, v117
	global_store_dwordx2 v161, v[176:177], s[98:99] offset:288
	v_mov_b32_e32 v114, v157
	v_add_u32_e32 v159, 0x100000, v158
	global_load_dwordx4 v[164:167], v159, s[100:101]
	global_load_dwordx4 v[168:171], v159, s[100:101] offset:64
	global_load_dwordx4 v[172:175], v159, s[100:101] offset:512
	global_load_dwordx4 v[176:179], v159, s[100:101] offset:576
	s_waitcnt vmcnt(16)
	v_add_u32_e32 v161, 0x10000, v160
	v_pk_add_f32 v[110:111], v[110:111], v[180:181]
	v_pk_add_f32 v[112:113], v[112:113], v[182:183]
	v_cvt_pk_bf16_f32 v180, v110, v111
	v_cvt_pk_bf16_f32 v181, v112, v113
	v_mul_f32_e32 v157, v110, v110
	v_fmac_f32_e32 v157, v111, v111
	v_fmac_f32_e32 v157, v112, v112
	v_fmac_f32_e32 v157, v113, v113
	global_store_dwordx2 v161, v[180:181], s[98:99]
	v_pk_add_f32 v[106:107], v[106:107], v[184:185]
	v_pk_add_f32 v[108:109], v[108:109], v[186:187]
	v_cvt_pk_bf16_f32 v184, v106, v107
	v_cvt_pk_bf16_f32 v185, v108, v109
	v_fmac_f32_e32 v157, v106, v106
	v_fmac_f32_e32 v157, v107, v107
	v_fmac_f32_e32 v157, v108, v108
	v_fmac_f32_e32 v157, v109, v109
	global_store_dwordx2 v161, v[184:185], s[98:99] offset:32
	v_pk_add_f32 v[102:103], v[102:103], v[188:189]
	v_pk_add_f32 v[104:105], v[104:105], v[190:191]
	v_cvt_pk_bf16_f32 v188, v102, v103
	v_cvt_pk_bf16_f32 v189, v104, v105
	v_fmac_f32_e32 v157, v102, v102
	v_fmac_f32_e32 v157, v103, v103
	v_fmac_f32_e32 v157, v104, v104
	v_fmac_f32_e32 v157, v105, v105
	global_store_dwordx2 v161, v[188:189], s[98:99] offset:256
	v_pk_add_f32 v[98:99], v[98:99], v[192:193]
	v_pk_add_f32 v[100:101], v[100:101], v[194:195]
	v_cvt_pk_bf16_f32 v192, v98, v99
	v_cvt_pk_bf16_f32 v193, v100, v101
	v_fmac_f32_e32 v157, v98, v98
	v_fmac_f32_e32 v157, v99, v99
	v_fmac_f32_e32 v157, v100, v100
	v_fmac_f32_e32 v157, v101, v101
	global_store_dwordx2 v161, v[192:193], s[98:99] offset:288
	v_mov_b32_e32 v98, v157
	v_add_u32_e32 v159, 0x120000, v158
	global_load_dwordx4 v[180:183], v159, s[100:101]
	global_load_dwordx4 v[184:187], v159, s[100:101] offset:64
	global_load_dwordx4 v[188:191], v159, s[100:101] offset:512
	global_load_dwordx4 v[192:195], v159, s[100:101] offset:576
	s_waitcnt vmcnt(20)
	v_add_u32_e32 v161, 0x20000, v160
	v_pk_add_f32 v[94:95], v[94:95], v[196:197]
	v_pk_add_f32 v[96:97], v[96:97], v[198:199]
	v_cvt_pk_bf16_f32 v196, v94, v95
	v_cvt_pk_bf16_f32 v197, v96, v97
	v_mul_f32_e32 v157, v94, v94
	v_fmac_f32_e32 v157, v95, v95
	v_fmac_f32_e32 v157, v96, v96
	v_fmac_f32_e32 v157, v97, v97
	global_store_dwordx2 v161, v[196:197], s[98:99]
	v_pk_add_f32 v[90:91], v[90:91], v[200:201]
	v_pk_add_f32 v[92:93], v[92:93], v[202:203]
	v_cvt_pk_bf16_f32 v200, v90, v91
	v_cvt_pk_bf16_f32 v201, v92, v93
	v_fmac_f32_e32 v157, v90, v90
	v_fmac_f32_e32 v157, v91, v91
	v_fmac_f32_e32 v157, v92, v92
	v_fmac_f32_e32 v157, v93, v93
	global_store_dwordx2 v161, v[200:201], s[98:99] offset:32
	v_pk_add_f32 v[86:87], v[86:87], v[204:205]
	v_pk_add_f32 v[88:89], v[88:89], v[206:207]
	v_cvt_pk_bf16_f32 v204, v86, v87
	v_cvt_pk_bf16_f32 v205, v88, v89
	v_fmac_f32_e32 v157, v86, v86
	v_fmac_f32_e32 v157, v87, v87
	v_fmac_f32_e32 v157, v88, v88
	v_fmac_f32_e32 v157, v89, v89
	global_store_dwordx2 v161, v[204:205], s[98:99] offset:256
	v_pk_add_f32 v[82:83], v[82:83], v[208:209]
	v_pk_add_f32 v[84:85], v[84:85], v[210:211]
	v_cvt_pk_bf16_f32 v208, v82, v83
	v_cvt_pk_bf16_f32 v209, v84, v85
	v_fmac_f32_e32 v157, v82, v82
	v_fmac_f32_e32 v157, v83, v83
	v_fmac_f32_e32 v157, v84, v84
	v_fmac_f32_e32 v157, v85, v85
	global_store_dwordx2 v161, v[208:209], s[98:99] offset:288
	v_mov_b32_e32 v82, v157
	v_add_u32_e32 v159, 0x140000, v158
	global_load_dwordx4 v[196:199], v159, s[100:101]
	global_load_dwordx4 v[200:203], v159, s[100:101] offset:64
	global_load_dwordx4 v[204:207], v159, s[100:101] offset:512
	global_load_dwordx4 v[208:211], v159, s[100:101] offset:576
	s_waitcnt vmcnt(24)
	v_add_u32_e32 v161, 0x30000, v160
	v_pk_add_f32 v[78:79], v[78:79], v[212:213]
	v_pk_add_f32 v[80:81], v[80:81], v[214:215]
	v_cvt_pk_bf16_f32 v212, v78, v79
	v_cvt_pk_bf16_f32 v213, v80, v81
	v_mul_f32_e32 v157, v78, v78
	v_fmac_f32_e32 v157, v79, v79
	v_fmac_f32_e32 v157, v80, v80
	v_fmac_f32_e32 v157, v81, v81
	global_store_dwordx2 v161, v[212:213], s[98:99]
	v_pk_add_f32 v[74:75], v[74:75], v[216:217]
	v_pk_add_f32 v[76:77], v[76:77], v[218:219]
	v_cvt_pk_bf16_f32 v216, v74, v75
	v_cvt_pk_bf16_f32 v217, v76, v77
	v_fmac_f32_e32 v157, v74, v74
	v_fmac_f32_e32 v157, v75, v75
	v_fmac_f32_e32 v157, v76, v76
	v_fmac_f32_e32 v157, v77, v77
	global_store_dwordx2 v161, v[216:217], s[98:99] offset:32
	v_pk_add_f32 v[70:71], v[70:71], v[220:221]
	v_pk_add_f32 v[72:73], v[72:73], v[222:223]
	v_cvt_pk_bf16_f32 v220, v70, v71
	v_cvt_pk_bf16_f32 v221, v72, v73
	v_fmac_f32_e32 v157, v70, v70
	v_fmac_f32_e32 v157, v71, v71
	v_fmac_f32_e32 v157, v72, v72
	v_fmac_f32_e32 v157, v73, v73
	global_store_dwordx2 v161, v[220:221], s[98:99] offset:256
	v_pk_add_f32 v[66:67], v[66:67], v[224:225]
	v_pk_add_f32 v[68:69], v[68:69], v[226:227]
	v_cvt_pk_bf16_f32 v224, v66, v67
	v_cvt_pk_bf16_f32 v225, v68, v69
	v_fmac_f32_e32 v157, v66, v66
	v_fmac_f32_e32 v157, v67, v67
	v_fmac_f32_e32 v157, v68, v68
	v_fmac_f32_e32 v157, v69, v69
	global_store_dwordx2 v161, v[224:225], s[98:99] offset:288
	v_mov_b32_e32 v66, v157
	v_add_u32_e32 v159, 0x160000, v158
	global_load_dwordx4 v[212:215], v159, s[100:101]
	global_load_dwordx4 v[216:219], v159, s[100:101] offset:64
	global_load_dwordx4 v[220:223], v159, s[100:101] offset:512
	global_load_dwordx4 v[224:227], v159, s[100:101] offset:576
	s_waitcnt vmcnt(24)
	v_add_u32_e32 v161, 0x80000, v160
	v_pk_add_f32 v[62:63], v[62:63], v[164:165]
	v_pk_add_f32 v[64:65], v[64:65], v[166:167]
	v_cvt_pk_bf16_f32 v164, v62, v63
	v_cvt_pk_bf16_f32 v165, v64, v65
	v_mul_f32_e32 v157, v62, v62
	v_fmac_f32_e32 v157, v63, v63
	v_fmac_f32_e32 v157, v64, v64
	v_fmac_f32_e32 v157, v65, v65
	global_store_dwordx2 v161, v[164:165], s[98:99]
	v_pk_add_f32 v[58:59], v[58:59], v[168:169]
	v_pk_add_f32 v[60:61], v[60:61], v[170:171]
	v_cvt_pk_bf16_f32 v168, v58, v59
	v_cvt_pk_bf16_f32 v169, v60, v61
	v_fmac_f32_e32 v157, v58, v58
	v_fmac_f32_e32 v157, v59, v59
	v_fmac_f32_e32 v157, v60, v60
	v_fmac_f32_e32 v157, v61, v61
	global_store_dwordx2 v161, v[168:169], s[98:99] offset:32
	v_pk_add_f32 v[54:55], v[54:55], v[172:173]
	v_pk_add_f32 v[56:57], v[56:57], v[174:175]
	v_cvt_pk_bf16_f32 v172, v54, v55
	v_cvt_pk_bf16_f32 v173, v56, v57
	v_fmac_f32_e32 v157, v54, v54
	v_fmac_f32_e32 v157, v55, v55
	v_fmac_f32_e32 v157, v56, v56
	v_fmac_f32_e32 v157, v57, v57
	global_store_dwordx2 v161, v[172:173], s[98:99] offset:256
	v_pk_add_f32 v[50:51], v[50:51], v[176:177]
	v_pk_add_f32 v[52:53], v[52:53], v[178:179]
	v_cvt_pk_bf16_f32 v176, v50, v51
	v_cvt_pk_bf16_f32 v177, v52, v53
	v_fmac_f32_e32 v157, v50, v50
	v_fmac_f32_e32 v157, v51, v51
	v_fmac_f32_e32 v157, v52, v52
	v_fmac_f32_e32 v157, v53, v53
	global_store_dwordx2 v161, v[176:177], s[98:99] offset:288
	v_mov_b32_e32 v50, v157
	s_waitcnt vmcnt(20)
	v_add_u32_e32 v161, 0x90000, v160
	v_pk_add_f32 v[46:47], v[46:47], v[180:181]
	v_pk_add_f32 v[48:49], v[48:49], v[182:183]
	v_cvt_pk_bf16_f32 v180, v46, v47
	v_cvt_pk_bf16_f32 v181, v48, v49
	v_mul_f32_e32 v157, v46, v46
	v_fmac_f32_e32 v157, v47, v47
	v_fmac_f32_e32 v157, v48, v48
	v_fmac_f32_e32 v157, v49, v49
	global_store_dwordx2 v161, v[180:181], s[98:99]
	v_pk_add_f32 v[42:43], v[42:43], v[184:185]
	v_pk_add_f32 v[44:45], v[44:45], v[186:187]
	v_cvt_pk_bf16_f32 v184, v42, v43
	v_cvt_pk_bf16_f32 v185, v44, v45
	v_fmac_f32_e32 v157, v42, v42
	v_fmac_f32_e32 v157, v43, v43
	v_fmac_f32_e32 v157, v44, v44
	v_fmac_f32_e32 v157, v45, v45
	global_store_dwordx2 v161, v[184:185], s[98:99] offset:32
	v_pk_add_f32 v[38:39], v[38:39], v[188:189]
	v_pk_add_f32 v[40:41], v[40:41], v[190:191]
	v_cvt_pk_bf16_f32 v188, v38, v39
	v_cvt_pk_bf16_f32 v189, v40, v41
	v_fmac_f32_e32 v157, v38, v38
	v_fmac_f32_e32 v157, v39, v39
	v_fmac_f32_e32 v157, v40, v40
	v_fmac_f32_e32 v157, v41, v41
	global_store_dwordx2 v161, v[188:189], s[98:99] offset:256
	v_pk_add_f32 v[34:35], v[34:35], v[192:193]
	v_pk_add_f32 v[36:37], v[36:37], v[194:195]
	v_cvt_pk_bf16_f32 v192, v34, v35
	v_cvt_pk_bf16_f32 v193, v36, v37
	v_fmac_f32_e32 v157, v34, v34
	v_fmac_f32_e32 v157, v35, v35
	v_fmac_f32_e32 v157, v36, v36
	v_fmac_f32_e32 v157, v37, v37
	global_store_dwordx2 v161, v[192:193], s[98:99] offset:288
	v_mov_b32_e32 v34, v157
	s_waitcnt vmcnt(16)
	v_add_u32_e32 v161, 0xa0000, v160
	v_pk_add_f32 v[30:31], v[30:31], v[196:197]
	v_pk_add_f32 v[32:33], v[32:33], v[198:199]
	v_cvt_pk_bf16_f32 v196, v30, v31
	v_cvt_pk_bf16_f32 v197, v32, v33
	v_mul_f32_e32 v157, v30, v30
	v_fmac_f32_e32 v157, v31, v31
	v_fmac_f32_e32 v157, v32, v32
	v_fmac_f32_e32 v157, v33, v33
	global_store_dwordx2 v161, v[196:197], s[98:99]
	v_pk_add_f32 v[26:27], v[26:27], v[200:201]
	v_pk_add_f32 v[28:29], v[28:29], v[202:203]
	v_cvt_pk_bf16_f32 v200, v26, v27
	v_cvt_pk_bf16_f32 v201, v28, v29
	v_fmac_f32_e32 v157, v26, v26
	v_fmac_f32_e32 v157, v27, v27
	v_fmac_f32_e32 v157, v28, v28
	v_fmac_f32_e32 v157, v29, v29
	global_store_dwordx2 v161, v[200:201], s[98:99] offset:32
	v_pk_add_f32 v[22:23], v[22:23], v[204:205]
	v_pk_add_f32 v[24:25], v[24:25], v[206:207]
	v_cvt_pk_bf16_f32 v204, v22, v23
	v_cvt_pk_bf16_f32 v205, v24, v25
	v_fmac_f32_e32 v157, v22, v22
	v_fmac_f32_e32 v157, v23, v23
	v_fmac_f32_e32 v157, v24, v24
	v_fmac_f32_e32 v157, v25, v25
	global_store_dwordx2 v161, v[204:205], s[98:99] offset:256
	v_pk_add_f32 v[18:19], v[18:19], v[208:209]
	v_pk_add_f32 v[20:21], v[20:21], v[210:211]
	v_cvt_pk_bf16_f32 v208, v18, v19
	v_cvt_pk_bf16_f32 v209, v20, v21
	v_fmac_f32_e32 v157, v18, v18
	v_fmac_f32_e32 v157, v19, v19
	v_fmac_f32_e32 v157, v20, v20
	v_fmac_f32_e32 v157, v21, v21
	global_store_dwordx2 v161, v[208:209], s[98:99] offset:288
	v_mov_b32_e32 v18, v157
	s_waitcnt vmcnt(12)
	v_add_u32_e32 v161, 0xb0000, v160
	v_pk_add_f32 v[14:15], v[14:15], v[212:213]
	v_pk_add_f32 v[16:17], v[16:17], v[214:215]
	v_cvt_pk_bf16_f32 v212, v14, v15
	v_cvt_pk_bf16_f32 v213, v16, v17
	v_mul_f32_e32 v157, v14, v14
	v_fmac_f32_e32 v157, v15, v15
	v_fmac_f32_e32 v157, v16, v16
	v_fmac_f32_e32 v157, v17, v17
	global_store_dwordx2 v161, v[212:213], s[98:99]
	v_pk_add_f32 v[10:11], v[10:11], v[216:217]
	v_pk_add_f32 v[12:13], v[12:13], v[218:219]
	v_cvt_pk_bf16_f32 v216, v10, v11
	v_cvt_pk_bf16_f32 v217, v12, v13
	v_fmac_f32_e32 v157, v10, v10
	v_fmac_f32_e32 v157, v11, v11
	v_fmac_f32_e32 v157, v12, v12
	v_fmac_f32_e32 v157, v13, v13
	global_store_dwordx2 v161, v[216:217], s[98:99] offset:32
	v_pk_add_f32 v[6:7], v[6:7], v[220:221]
	v_pk_add_f32 v[8:9], v[8:9], v[222:223]
	v_cvt_pk_bf16_f32 v220, v6, v7
	v_cvt_pk_bf16_f32 v221, v8, v9
	v_fmac_f32_e32 v157, v6, v6
	v_fmac_f32_e32 v157, v7, v7
	v_fmac_f32_e32 v157, v8, v8
	v_fmac_f32_e32 v157, v9, v9
	global_store_dwordx2 v161, v[220:221], s[98:99] offset:256
	v_pk_add_f32 v[2:3], v[2:3], v[224:225]
	v_pk_add_f32 v[4:5], v[4:5], v[226:227]
	v_cvt_pk_bf16_f32 v224, v2, v3
	v_cvt_pk_bf16_f32 v225, v4, v5
	v_fmac_f32_e32 v157, v2, v2
	v_fmac_f32_e32 v157, v3, v3
	v_fmac_f32_e32 v157, v4, v4
	v_fmac_f32_e32 v157, v5, v5
	global_store_dwordx2 v161, v[224:225], s[98:99] offset:288
	v_mov_b32_e32 v2, v157
	ds_bpermute_b32 v115, v162, v114
	ds_bpermute_b32 v99, v162, v98
	ds_bpermute_b32 v83, v162, v82
	ds_bpermute_b32 v67, v162, v66
	ds_bpermute_b32 v51, v162, v50
	ds_bpermute_b32 v35, v162, v34
	ds_bpermute_b32 v19, v162, v18
	ds_bpermute_b32 v3, v162, v2
	s_waitcnt lgkmcnt(0)
	v_add_f32_e32 v114, v114, v115
	v_add_f32_e32 v98, v98, v99
	v_add_f32_e32 v82, v82, v83
	v_add_f32_e32 v66, v66, v67
	v_add_f32_e32 v50, v50, v51
	v_add_f32_e32 v34, v34, v35
	v_add_f32_e32 v18, v18, v19
	v_add_f32_e32 v2, v2, v3
	ds_bpermute_b32 v115, v163, v114
	ds_bpermute_b32 v99, v163, v98
	ds_bpermute_b32 v83, v163, v82
	ds_bpermute_b32 v67, v163, v66
	ds_bpermute_b32 v51, v163, v50
	ds_bpermute_b32 v35, v163, v34
	ds_bpermute_b32 v19, v163, v18
	ds_bpermute_b32 v3, v163, v2
	s_waitcnt lgkmcnt(0)
	v_add_f32_e32 v114, v114, v115
	v_add_f32_e32 v98, v98, v99
	v_add_f32_e32 v82, v82, v83
	v_add_f32_e32 v66, v66, v67
	v_add_f32_e32 v50, v50, v51
	v_add_f32_e32 v34, v34, v35
	v_add_f32_e32 v18, v18, v19
	v_add_f32_e32 v2, v2, v3
	s_and_saveexec_b64 vcc, s[0:1]
	s_cbranch_execz .Lout_epi_noatom
	global_atomic_add_f32 v145, v114, s[96:97]
	global_atomic_add_f32 v145, v98, s[96:97] offset:64
	global_atomic_add_f32 v145, v82, s[96:97] offset:128
	global_atomic_add_f32 v145, v66, s[96:97] offset:192
	global_atomic_add_f32 v145, v50, s[96:97] offset:512
	global_atomic_add_f32 v145, v34, s[96:97] offset:576
	global_atomic_add_f32 v145, v18, s[96:97] offset:640
	global_atomic_add_f32 v145, v2, s[96:97] offset:704
.Lout_epi_noatom:
	s_or_b64 exec, exec, vcc
	s_andn2_b64 vcc, exec, s[4:5]
	s_mov_b64 s[4:5], -1
	s_cbranch_vccnz .LBB0_549
	s_andn2_b64 vcc, exec, s[2:3]
	s_cbranch_vccnz .LBB0_548
	s_barrier
	s_branch .LBB0_548
